# mixer-in V^T/T tiles staged through LDS (pair-packed ds_write_b32, 16-byte write-through stores); with every consumer-visible store of that phase write-through the barrier after it no longer needs buf
# speedup vs baseline: 1.0011x; 1.0011x over previous
.LBB0_597:
	s_sub_u32 s27, s8, 4
	s_cmp_lt_u32 s27, 4
	s_cbranch_scc1 .Lmx_entry
	s_cmp_lt_i32 s6, 16
	s_cselect_b64 s[4:5], -1, 0
	s_cmp_gt_i32 s8, 1
	s_cselect_b64 s[42:43], -1, 0
	s_cmp_gt_u32 s8, 3
	v_sub_co_u32_e64 v128, s[26:27], s8, 6
	s_cselect_b64 s[54:55], -1, 0
	s_xor_b64 s[60:61], s[26:27], -1
	s_cmp_gt_u32 s8, 7
	s_cselect_b64 s[58:59], -1, 0
	s_lshl_b32 s8, s8, 8
	s_add_i32 s38, s8, 0xfffff800
	s_lshl_b64 s[26:27], s[38:39], 1
	s_add_u32 s64, s41, s26
	s_addc_u32 s65, s33, s27
	s_ashr_i32 s9, s8, 31
	s_add_i32 s93, s8, 0xfffffc00
	s_add_i32 s91, s8, 0xfffffe00
	s_lshl_b64 s[8:9], s[8:9], 1
	s_add_u32 s62, s85, s8
	s_addc_u32 s63, s53, s9
	s_lshl_b32 s95, s6, 8
	v_lshlrev_b32_e32 v144, 11, v128
	s_add_i32 s95, s95, s75
	v_lshl_add_u64 v[168:169], s[88:89], 0, v[144:145]
	v_lshlrev_b32_e32 v144, 9, v128
	v_or_b32_e32 v128, s95, v140
	s_add_i32 s7, s95, 0xfffff000
	v_bitop3_b32 v131, s95, v195, v140 bitop3:0xc8
	v_lshl_add_u64 v[166:167], s[22:23], 0, v[144:145]
	s_ashr_i32 s7, s7, 10
	v_bitop3_b32 v130, s95, v194, v140 bitop3:0xc8
	v_ashrrev_i32_e32 v129, 31, v128
	v_lshlrev_b32_e32 v144, 1, v131
	s_ashr_i32 s6, s95, 8
	v_lshlrev_b64 v[180:181], 10, v[128:129]
	v_lshl_add_u64 v[174:175], v[168:169], 0, v[144:145]
	v_lshlrev_b32_e32 v144, 1, v130
	s_lshl_b32 s31, s7, 7
	v_bfe_u32 v128, v128, 6, 4
	v_lshl_add_u64 v[176:177], v[166:167], 0, v[144:145]
	v_lshlrev_b32_e32 v144, 11, v130
	v_or_b32_e32 v161, s31, v128
	s_lshl_b32 s36, s6, 6
	v_lshrrev_b32_e32 v128, 5, v130
	s_lshl_b32 s37, s7, 13
	s_lshl_b32 s26, s6, 11
	s_mov_b64 s[44:45], -1
	v_lshl_add_u64 v[178:179], s[64:65], 0, v[180:181]
	s_lshl_b32 s40, s7, 8
	s_and_b32 s30, s95, 0xffffff00
	s_lshl_b32 s73, s6, 2
	v_lshl_add_u64 v[172:173], s[12:13], 0, v[144:145]
	v_or_b32_e32 v203, s36, v128
	v_or_b32_e32 v157, s37, v131
	v_or_b32_e32 v159, s26, v130
	v_lshl_add_u64 v[170:171], s[24:25], 0, v[144:145]
	s_and_b64 vcc, exec, s[42:43]
	s_cbranch_vccz .LBB0_615
	s_mov_b64 s[6:7], -1
	s_and_b64 vcc, exec, s[54:55]
	s_cbranch_vccz .LBB0_611
	s_and_b64 vcc, exec, s[60:61]
	s_cbranch_vccz .LBB0_605
	s_and_b64 vcc, exec, s[58:59]
	s_cbranch_vccz .LBB0_602
	v_mul_f32_e32 v128, 0x3d372713, v124
	v_mul_f32_e32 v128, v124, v128
	v_fma_f32 v128, v124, v128, v124
	v_mul_f32_e32 v128, 0x3f4c422a, v128
	v_add_f32_e32 v128, v128, v128
	v_mul_f32_e32 v128, 0x3fb8aa3b, v128
	v_exp_f32_e32 v128, v128
	v_mul_f32_e32 v129, 0.5, v124
	v_mul_f32_e32 v130, 0.5, v125
	v_mul_f32_e32 v131, 0.5, v127
	v_add_f32_e32 v128, 1.0, v128
	v_rcp_f32_e32 v128, v128
	v_mul_f32_e32 v144, 0.5, v121
	v_mul_f32_e32 v190, 0.5, v123
	s_mov_b64 s[6:7], 0
	v_fma_f32 v128, v128, -2.0, 1.0
	v_add_f32_e32 v128, 1.0, v128
	v_mul_f32_e32 v128, v129, v128
	v_mul_f32_e32 v129, 0x3d372713, v125
	v_mul_f32_e32 v129, v125, v129
	v_fma_f32 v129, v125, v129, v125
	v_mul_f32_e32 v129, 0x3f4c422a, v129
	v_add_f32_e32 v129, v129, v129
	v_mul_f32_e32 v129, 0x3fb8aa3b, v129
	v_exp_f32_e32 v129, v129
	s_nop 0
	v_add_f32_e32 v129, 1.0, v129
	v_rcp_f32_e32 v129, v129
	s_nop 0
	v_fma_f32 v129, v129, -2.0, 1.0
	v_add_f32_e32 v129, 1.0, v129
	v_mul_f32_e32 v129, v130, v129
	v_cvt_pk_bf16_f32 v128, v128, v129
	v_mul_f32_e32 v129, 0x3d372713, v126
	v_mul_f32_e32 v129, v126, v129
	v_fma_f32 v129, v126, v129, v126
	v_mul_f32_e32 v129, 0x3f4c422a, v129
	v_add_f32_e32 v129, v129, v129
	v_mul_f32_e32 v129, 0x3fb8aa3b, v129
	v_exp_f32_e32 v129, v129
	v_mul_f32_e32 v130, 0.5, v126
	v_add_f32_e32 v129, 1.0, v129
	v_rcp_f32_e32 v129, v129
	s_nop 0
	v_fma_f32 v129, v129, -2.0, 1.0
	v_add_f32_e32 v129, 1.0, v129
	v_mul_f32_e32 v129, v130, v129
	v_mul_f32_e32 v130, 0x3d372713, v127
	v_mul_f32_e32 v130, v127, v130
	v_fma_f32 v130, v127, v130, v127
	v_mul_f32_e32 v130, 0x3f4c422a, v130
	v_add_f32_e32 v130, v130, v130
	v_mul_f32_e32 v130, 0x3fb8aa3b, v130
	v_exp_f32_e32 v130, v130
	s_nop 0
	v_add_f32_e32 v130, 1.0, v130
	v_rcp_f32_e32 v130, v130
	s_nop 0
	v_fma_f32 v130, v130, -2.0, 1.0
	v_add_f32_e32 v130, 1.0, v130
	v_mul_f32_e32 v130, v131, v130
	v_cvt_pk_bf16_f32 v129, v129, v130
	v_mul_f32_e32 v130, 0x3d372713, v120
	v_mul_f32_e32 v130, v120, v130
	v_fma_f32 v130, v120, v130, v120
	v_mul_f32_e32 v130, 0x3f4c422a, v130
	v_add_f32_e32 v130, v130, v130
	v_mul_f32_e32 v130, 0x3fb8aa3b, v130
	v_exp_f32_e32 v130, v130
	v_mul_f32_e32 v131, 0.5, v120
	v_add_f32_e32 v130, 1.0, v130
	v_rcp_f32_e32 v130, v130
	s_nop 0
	v_fma_f32 v130, v130, -2.0, 1.0
	v_add_f32_e32 v130, 1.0, v130
	v_mul_f32_e32 v130, v131, v130
	v_mul_f32_e32 v131, 0x3d372713, v121
	v_mul_f32_e32 v131, v121, v131
	v_fma_f32 v131, v121, v131, v121
	v_mul_f32_e32 v131, 0x3f4c422a, v131
	v_add_f32_e32 v131, v131, v131
	v_mul_f32_e32 v131, 0x3fb8aa3b, v131
	v_exp_f32_e32 v131, v131
	s_nop 0
	v_add_f32_e32 v131, 1.0, v131
	v_rcp_f32_e32 v131, v131
	s_nop 0
	v_fma_f32 v131, v131, -2.0, 1.0
	v_add_f32_e32 v131, 1.0, v131
	v_mul_f32_e32 v131, v144, v131
	v_cvt_pk_bf16_f32 v130, v130, v131
	v_mul_f32_e32 v131, 0x3d372713, v122
	v_mul_f32_e32 v131, v122, v131
	v_fma_f32 v131, v122, v131, v122
	v_mul_f32_e32 v131, 0x3f4c422a, v131
	v_add_f32_e32 v131, v131, v131
	v_mul_f32_e32 v131, 0x3fb8aa3b, v131
	v_exp_f32_e32 v131, v131
	v_mul_f32_e32 v144, 0.5, v122
	v_add_f32_e32 v131, 1.0, v131
	v_rcp_f32_e32 v131, v131
	s_nop 0
	v_fma_f32 v131, v131, -2.0, 1.0
	v_add_f32_e32 v131, 1.0, v131
	v_mul_f32_e32 v131, v144, v131
	v_mul_f32_e32 v144, 0x3d372713, v123
	v_mul_f32_e32 v144, v123, v144
	v_fma_f32 v144, v123, v144, v123
	v_mul_f32_e32 v144, 0x3f4c422a, v144
	v_add_f32_e32 v144, v144, v144
	v_mul_f32_e32 v144, 0x3fb8aa3b, v144
	v_exp_f32_e32 v144, v144
	s_nop 0
	v_add_f32_e32 v144, 1.0, v144
	v_rcp_f32_e32 v144, v144
	s_nop 0
	v_fma_f32 v144, v144, -2.0, 1.0
	v_add_f32_e32 v144, 1.0, v144
	v_mul_f32_e32 v144, v190, v144
	v_cvt_pk_bf16_f32 v131, v131, v144
	v_lshlrev_b32_e32 v144, 1, v142
	v_lshl_add_u64 v[190:191], v[178:179], 0, v[144:145]
	global_store_dwordx4 v[190:191], v[128:131], off sc1

.Lmx_entry:
	s_load_dwordx2 s[4:5], s[16:17], 0x90
	s_load_dwordx2 s[42:43], s[16:17], 0x98
	v_readfirstlane_b32 s27, v147
	v_and_b32_e32 v172, 63, v147
	s_lshr_b32 s27, s27, 6
	s_lshr_b32 s30, s27, 2
	s_and_b32 s32, s27, 3
	v_lshrrev_b32_e32 v168, 4, v172
	v_mul_u32_u24_e32 v168, 0x440, v168
	v_and_b32_e32 v171, 15, v172
	v_lshl_add_u32 v168, v171, 1, v168
	s_mul_i32 s91, s27, 0x1200
	v_add_u32_e32 v168, s91, v168
	v_and_b32_e32 v239, 1, v172
	v_cmp_eq_u32_e32 vcc, 0, v239
	v_mov_b32_e32 v238, 0x03020706
	v_mov_b32_e32 v175, 0x05040100
	v_cndmask_b32_e32 v238, v238, v175, vcc
	v_mul_u32_u24_e32 v175, 0x86, v239
	v_add_u32_e32 v239, v168, v175
	v_lshrrev_b32_e32 v169, 3, v172
	v_mul_u32_u24_e32 v169, 0x88, v169
	v_and_b32_e32 v170, 7, v172
	v_lshl_add_u32 v169, v170, 4, v169
	v_add_u32_e32 v169, s91, v169
	v_lshlrev_b32_e32 v171, 11, v171
	v_lshrrev_b32_e32 v174, 4, v172
	v_lshl_add_u32 v171, v174, 5, v171
	s_sub_u32 s91, s6, 16
	s_lshr_b32 s93, s91, 2
	s_and_b32 s91, s91, 3
	s_cmp_lt_u32 s8, 6
	s_cbranch_scc0 .Lmx_T
	s_sub_u32 s37, s8, 4
	s_lshl_b32 s37, s37, 2
	s_lshr_b32 s55, s32, 1
	s_add_u32 s37, s37, s55
	s_and_b32 s73, s32, 1
	s_cmp_lt_u32 s6, 16
	s_cbranch_scc0 .Lmx_Vs
	s_lshl_b32 s55, s6, 3
	s_add_u32 s37, s37, s55
	s_lshl_b32 s37, s37, 14
	s_lshl_b32 s55, s30, 12
	s_add_u32 s37, s37, s55
	s_lshl_b32 s73, s73, 10
	s_add_u32 s37, s37, s73
	s_mov_b32 s40, 6
	s_mov_b32 s55, 0x4000
	s_mov_b32 s73, 0x10000
	s_mov_b32 s95, 1
	s_movk_i32 s101, 0x1000
	s_mov_b32 s91, 0x3000000
	s_branch .Lmx_setup_done
.Lmx_Vs:
	s_lshl_b32 s55, s93, 3
	s_add_u32 s37, s37, s55
	s_lshl_b32 s37, s37, 16
	s_lshl_b32 s55, s91, 2
	s_add_u32 s55, s55, s30
	s_lshl_b32 s55, s55, 12
	s_add_u32 s37, s37, s55
	s_lshl_b32 s73, s73, 11
	s_add_u32 s37, s37, s73
	s_add_u32 s37, s37, 0x200000
	s_mov_b32 s40, 7
	s_mov_b32 s55, 0x4000
	s_mov_b32 s73, 0x40000
	s_mov_b32 s95, 0
	s_movk_i32 s101, 0x40
	s_mov_b32 s91, 0x3000000
	s_branch .Lmx_setup_done
.Lmx_T:
	s_sub_u32 s37, s8, 6
	s_lshl_b32 s73, s32, 5
	s_lshl_b32 s55, s30, 6
	s_cmp_lt_u32 s6, 16
	s_cbranch_scc0 .Lmx_Ts
	s_lshl_b32 s37, s37, 8
	s_add_u32 s37, s37, s55
	s_lshl_b32 s55, s6, 8
	s_add_u32 s55, s55, s73
	s_lshl_b32 s55, s55, 9
	s_add_u32 s37, s37, s55
	s_mov_b32 s40, 10
	s_mov_b32 s55, 0x100
	s_mov_b32 s73, 0x20000
	s_mov_b32 s95, 0
	s_movk_i32 s101, 0x40
	s_mov_b32 s91, 0x3800000
	s_branch .Lmx_setup_done
.Lmx_Ts:
	s_lshl_b32 s37, s37, 10
	s_add_u32 s37, s37, s55
	s_lshl_b32 s55, s91, 8
	s_add_u32 s37, s37, s55
	s_lshl_b32 s55, s93, 8
	s_add_u32 s55, s55, s73
	s_lshl_b32 s55, s55, 11
	s_add_u32 s37, s37, s55
	s_add_u32 s37, s37, 0x200000
	s_mov_b32 s40, 12
	s_mov_b32 s55, 0x100
	s_mov_b32 s73, 0x80000
	s_mov_b32 s95, 0
	s_movk_i32 s101, 0x40
	s_mov_b32 s91, 0x3800000
.Lmx_setup_done:
	v_lshrrev_b32_e32 v174, 3, v172
	v_lshlrev_b32_e32 v174, s40, v174
	v_lshrrev_b32_e32 v175, 2, v170
	v_mul_u32_u24_e32 v175, s101, v175
	v_and_b32_e32 v170, 3, v170
	v_lshl_add_u32 v170, v170, 4, v175
	v_add_u32_e32 v170, v174, v170
	s_lshl_b32 s100, 8, s40
	s_waitcnt lgkmcnt(0)
	s_lshl_b32 s37, s37, 1
	s_add_u32 s37, s37, s91
	s_add_u32 s58, s42, s37
	s_addc_u32 s59, s43, 0
	s_lshl_b32 s91, s6, 2
	s_add_u32 s91, s91, s70
	s_lshl_b32 s91, s91, 8
	s_lshl_b32 s93, s30, 6
	s_add_u32 s91, s91, s93
	s_lshl_b32 s91, s91, 11
	s_sub_u32 s93, s8, 4
	s_lshl_b32 s93, s93, 8
	s_lshl_b32 s37, s32, 5
	s_add_u32 s93, s93, s37
	s_lshl_b32 s93, s93, 2
	s_add_u32 s91, s91, s93
	s_add_u32 s91, s91, 0x4000000
	s_add_u32 s60, s4, s91
	s_addc_u32 s61, s5, 0
	s_waitcnt vmcnt(0)
	s_barrier
	s_cmp_eq_u32 s95, 0
	s_cbranch_scc1 .Lmx_00_nonv
	s_mov_b64 s[62:63], s[60:61]
	global_store_dwordx4 v171, v[124:127], s[62:63] nt
	global_store_dwordx4 v171, v[120:123], s[62:63] offset:16 nt
	s_add_u32 s62, s62, 0x8000
	s_addc_u32 s63, s63, 0
	global_store_dwordx4 v171, v[108:111], s[62:63] nt
	global_store_dwordx4 v171, v[104:107], s[62:63] offset:16 nt
	s_add_u32 s62, s62, 0x8000
	s_addc_u32 s63, s63, 0
	global_store_dwordx4 v171, v[92:95], s[62:63] nt
	global_store_dwordx4 v171, v[88:91], s[62:63] offset:16 nt
	s_add_u32 s62, s62, 0x8000
	s_addc_u32 s63, s63, 0
	global_store_dwordx4 v171, v[76:79], s[62:63] nt
	global_store_dwordx4 v171, v[72:75], s[62:63] offset:16 nt
.Lmx_00_nonv:
	v_cvt_pk_bf16_f32 v174, v124, v125
	v_cvt_pk_bf16_f32 v175, v126, v127
	v_cvt_pk_bf16_f32 v176, v120, v121
	v_cvt_pk_bf16_f32 v177, v122, v123
	v_mov_b32_dpp v230, v174 quad_perm:[1,0,3,2] row_mask:0xf bank_mask:0xf
	v_mov_b32_dpp v231, v175 quad_perm:[1,0,3,2] row_mask:0xf bank_mask:0xf
	v_mov_b32_dpp v232, v176 quad_perm:[1,0,3,2] row_mask:0xf bank_mask:0xf
	v_mov_b32_dpp v233, v177 quad_perm:[1,0,3,2] row_mask:0xf bank_mask:0xf
	v_perm_b32 v230, v230, v174, v238
	v_perm_b32 v231, v231, v175, v238
	v_perm_b32 v232, v232, v176, v238
	v_perm_b32 v233, v233, v177, v238
	ds_write_b32 v239, v230 offset:0
	ds_write_b32 v239, v231 offset:272
	ds_write_b32 v239, v232 offset:544
	ds_write_b32 v239, v233 offset:816
	v_cvt_pk_bf16_f32 v178, v108, v109
	v_cvt_pk_bf16_f32 v179, v110, v111
	v_cvt_pk_bf16_f32 v180, v104, v105
	v_cvt_pk_bf16_f32 v181, v106, v107
	v_mov_b32_dpp v234, v178 quad_perm:[1,0,3,2] row_mask:0xf bank_mask:0xf
	v_mov_b32_dpp v235, v179 quad_perm:[1,0,3,2] row_mask:0xf bank_mask:0xf
	v_mov_b32_dpp v236, v180 quad_perm:[1,0,3,2] row_mask:0xf bank_mask:0xf
	v_mov_b32_dpp v237, v181 quad_perm:[1,0,3,2] row_mask:0xf bank_mask:0xf
	v_perm_b32 v234, v234, v178, v238
	v_perm_b32 v235, v235, v179, v238
	v_perm_b32 v236, v236, v180, v238
	v_perm_b32 v237, v237, v181, v238
	ds_write_b32 v239, v234 offset:32
	ds_write_b32 v239, v235 offset:304
	ds_write_b32 v239, v236 offset:576
	ds_write_b32 v239, v237 offset:848
	v_cvt_pk_bf16_f32 v174, v92, v93
	v_cvt_pk_bf16_f32 v175, v94, v95
	v_cvt_pk_bf16_f32 v176, v88, v89
	v_cvt_pk_bf16_f32 v177, v90, v91
	v_mov_b32_dpp v230, v174 quad_perm:[1,0,3,2] row_mask:0xf bank_mask:0xf
	v_mov_b32_dpp v231, v175 quad_perm:[1,0,3,2] row_mask:0xf bank_mask:0xf
	v_mov_b32_dpp v232, v176 quad_perm:[1,0,3,2] row_mask:0xf bank_mask:0xf
	v_mov_b32_dpp v233, v177 quad_perm:[1,0,3,2] row_mask:0xf bank_mask:0xf
	v_perm_b32 v230, v230, v174, v238
	v_perm_b32 v231, v231, v175, v238
	v_perm_b32 v232, v232, v176, v238
	v_perm_b32 v233, v233, v177, v238
	ds_write_b32 v239, v230 offset:64
	ds_write_b32 v239, v231 offset:336
	ds_write_b32 v239, v232 offset:608
	ds_write_b32 v239, v233 offset:880
	v_cvt_pk_bf16_f32 v178, v76, v77
	v_cvt_pk_bf16_f32 v179, v78, v79
	v_cvt_pk_bf16_f32 v180, v72, v73
	v_cvt_pk_bf16_f32 v181, v74, v75
	v_mov_b32_dpp v234, v178 quad_perm:[1,0,3,2] row_mask:0xf bank_mask:0xf
	v_mov_b32_dpp v235, v179 quad_perm:[1,0,3,2] row_mask:0xf bank_mask:0xf
	v_mov_b32_dpp v236, v180 quad_perm:[1,0,3,2] row_mask:0xf bank_mask:0xf
	v_mov_b32_dpp v237, v181 quad_perm:[1,0,3,2] row_mask:0xf bank_mask:0xf
	v_perm_b32 v234, v234, v178, v238
	v_perm_b32 v235, v235, v179, v238
	v_perm_b32 v236, v236, v180, v238
	v_perm_b32 v237, v237, v181, v238
	ds_write_b32 v239, v234 offset:96
	ds_write_b32 v239, v235 offset:368
	ds_write_b32 v239, v236 offset:640
	ds_write_b32 v239, v237 offset:912
	s_waitcnt lgkmcnt(0)
	ds_read_b64 v[214:215], v169 offset:0
	ds_read_b64 v[216:217], v169 offset:8
	ds_read_b64 v[218:219], v169 offset:1088
	ds_read_b64 v[220:221], v169 offset:1096
	ds_read_b64 v[222:223], v169 offset:2176
	ds_read_b64 v[224:225], v169 offset:2184
	ds_read_b64 v[226:227], v169 offset:3264
	ds_read_b64 v[228:229], v169 offset:3272
	s_mov_b64 s[62:63], s[58:59]
	s_waitcnt lgkmcnt(6)
	global_store_dwordx4 v170, v[214:217], s[62:63] sc1
	s_add_u32 s62, s62, s100
	s_addc_u32 s63, s63, 0
	s_waitcnt lgkmcnt(4)
	global_store_dwordx4 v170, v[218:221], s[62:63] sc1
	s_add_u32 s62, s62, s100
	s_addc_u32 s63, s63, 0
	s_waitcnt lgkmcnt(2)
	global_store_dwordx4 v170, v[222:225], s[62:63] sc1
	s_add_u32 s62, s62, s100
	s_addc_u32 s63, s63, 0
	s_waitcnt lgkmcnt(0)
	global_store_dwordx4 v170, v[226:229], s[62:63] sc1
	s_cmp_eq_u32 s95, 0
	s_cbranch_scc1 .Lmx_01_nonv
	s_add_u32 s62, s60, 0x200
	s_addc_u32 s63, s61, 0
	global_store_dwordx4 v171, v[116:119], s[62:63] nt
	global_store_dwordx4 v171, v[112:115], s[62:63] offset:16 nt
	s_add_u32 s62, s62, 0x8000
	s_addc_u32 s63, s63, 0
	global_store_dwordx4 v171, v[100:103], s[62:63] nt
	global_store_dwordx4 v171, v[96:99], s[62:63] offset:16 nt
	s_add_u32 s62, s62, 0x8000
	s_addc_u32 s63, s63, 0
	global_store_dwordx4 v171, v[84:87], s[62:63] nt
	global_store_dwordx4 v171, v[80:83], s[62:63] offset:16 nt
	s_add_u32 s62, s62, 0x8000
	s_addc_u32 s63, s63, 0
	global_store_dwordx4 v171, v[68:71], s[62:63] nt
	global_store_dwordx4 v171, v[64:67], s[62:63] offset:16 nt
.Lmx_01_nonv:
	v_cvt_pk_bf16_f32 v174, v116, v117
	v_cvt_pk_bf16_f32 v175, v118, v119
	v_cvt_pk_bf16_f32 v176, v112, v113
	v_cvt_pk_bf16_f32 v177, v114, v115
	v_mov_b32_dpp v230, v174 quad_perm:[1,0,3,2] row_mask:0xf bank_mask:0xf
	v_mov_b32_dpp v231, v175 quad_perm:[1,0,3,2] row_mask:0xf bank_mask:0xf
	v_mov_b32_dpp v232, v176 quad_perm:[1,0,3,2] row_mask:0xf bank_mask:0xf
	v_mov_b32_dpp v233, v177 quad_perm:[1,0,3,2] row_mask:0xf bank_mask:0xf
	v_perm_b32 v230, v230, v174, v238
	v_perm_b32 v231, v231, v175, v238
	v_perm_b32 v232, v232, v176, v238
	v_perm_b32 v233, v233, v177, v238
	ds_write_b32 v239, v230 offset:0
	ds_write_b32 v239, v231 offset:272
	ds_write_b32 v239, v232 offset:544
	ds_write_b32 v239, v233 offset:816
	v_cvt_pk_bf16_f32 v178, v100, v101
	v_cvt_pk_bf16_f32 v179, v102, v103
	v_cvt_pk_bf16_f32 v180, v96, v97
	v_cvt_pk_bf16_f32 v181, v98, v99
	v_mov_b32_dpp v234, v178 quad_perm:[1,0,3,2] row_mask:0xf bank_mask:0xf
	v_mov_b32_dpp v235, v179 quad_perm:[1,0,3,2] row_mask:0xf bank_mask:0xf
	v_mov_b32_dpp v236, v180 quad_perm:[1,0,3,2] row_mask:0xf bank_mask:0xf
	v_mov_b32_dpp v237, v181 quad_perm:[1,0,3,2] row_mask:0xf bank_mask:0xf
	v_perm_b32 v234, v234, v178, v238
	v_perm_b32 v235, v235, v179, v238
	v_perm_b32 v236, v236, v180, v238
	v_perm_b32 v237, v237, v181, v238
	ds_write_b32 v239, v234 offset:32
	ds_write_b32 v239, v235 offset:304
	ds_write_b32 v239, v236 offset:576
	ds_write_b32 v239, v237 offset:848
	v_cvt_pk_bf16_f32 v174, v84, v85
	v_cvt_pk_bf16_f32 v175, v86, v87
	v_cvt_pk_bf16_f32 v176, v80, v81
	v_cvt_pk_bf16_f32 v177, v82, v83
	v_mov_b32_dpp v230, v174 quad_perm:[1,0,3,2] row_mask:0xf bank_mask:0xf
	v_mov_b32_dpp v231, v175 quad_perm:[1,0,3,2] row_mask:0xf bank_mask:0xf
	v_mov_b32_dpp v232, v176 quad_perm:[1,0,3,2] row_mask:0xf bank_mask:0xf
	v_mov_b32_dpp v233, v177 quad_perm:[1,0,3,2] row_mask:0xf bank_mask:0xf
	v_perm_b32 v230, v230, v174, v238
	v_perm_b32 v231, v231, v175, v238
	v_perm_b32 v232, v232, v176, v238
	v_perm_b32 v233, v233, v177, v238
	ds_write_b32 v239, v230 offset:64
	ds_write_b32 v239, v231 offset:336
	ds_write_b32 v239, v232 offset:608
	ds_write_b32 v239, v233 offset:880
	v_cvt_pk_bf16_f32 v178, v68, v69
	v_cvt_pk_bf16_f32 v179, v70, v71
	v_cvt_pk_bf16_f32 v180, v64, v65
	v_cvt_pk_bf16_f32 v181, v66, v67
	v_mov_b32_dpp v234, v178 quad_perm:[1,0,3,2] row_mask:0xf bank_mask:0xf
	v_mov_b32_dpp v235, v179 quad_perm:[1,0,3,2] row_mask:0xf bank_mask:0xf
	v_mov_b32_dpp v236, v180 quad_perm:[1,0,3,2] row_mask:0xf bank_mask:0xf
	v_mov_b32_dpp v237, v181 quad_perm:[1,0,3,2] row_mask:0xf bank_mask:0xf
	v_perm_b32 v234, v234, v178, v238
	v_perm_b32 v235, v235, v179, v238
	v_perm_b32 v236, v236, v180, v238
	v_perm_b32 v237, v237, v181, v238
	ds_write_b32 v239, v234 offset:96
	ds_write_b32 v239, v235 offset:368
	ds_write_b32 v239, v236 offset:640
	ds_write_b32 v239, v237 offset:912
	s_waitcnt lgkmcnt(0)
	ds_read_b64 v[214:215], v169 offset:0
	ds_read_b64 v[216:217], v169 offset:8
	ds_read_b64 v[218:219], v169 offset:1088
	ds_read_b64 v[220:221], v169 offset:1096
	ds_read_b64 v[222:223], v169 offset:2176
	ds_read_b64 v[224:225], v169 offset:2184
	ds_read_b64 v[226:227], v169 offset:3264
	ds_read_b64 v[228:229], v169 offset:3272
	s_mov_b64 s[62:63], s[58:59]
	s_add_u32 s62, s62, s73
	s_addc_u32 s63, s63, 0
	s_waitcnt lgkmcnt(6)
	global_store_dwordx4 v170, v[214:217], s[62:63] sc1
	s_add_u32 s62, s62, s100
	s_addc_u32 s63, s63, 0
	s_waitcnt lgkmcnt(4)
	global_store_dwordx4 v170, v[218:221], s[62:63] sc1
	s_add_u32 s62, s62, s100
	s_addc_u32 s63, s63, 0
	s_waitcnt lgkmcnt(2)
	global_store_dwordx4 v170, v[222:225], s[62:63] sc1
	s_add_u32 s62, s62, s100
	s_addc_u32 s63, s63, 0
	s_waitcnt lgkmcnt(0)
	global_store_dwordx4 v170, v[226:229], s[62:63] sc1
	s_cmp_eq_u32 s95, 0
	s_cbranch_scc1 .Lmx_10_nonv
	s_add_u32 s62, s60, 0x40000
	s_addc_u32 s63, s61, 0
	global_store_dwordx4 v171, v[60:63], s[62:63] nt
	global_store_dwordx4 v171, v[56:59], s[62:63] offset:16 nt
	s_add_u32 s62, s62, 0x8000
	s_addc_u32 s63, s63, 0
	global_store_dwordx4 v171, v[44:47], s[62:63] nt
	global_store_dwordx4 v171, v[40:43], s[62:63] offset:16 nt
	s_add_u32 s62, s62, 0x8000
	s_addc_u32 s63, s63, 0
	global_store_dwordx4 v171, v[28:31], s[62:63] nt
	global_store_dwordx4 v171, v[24:27], s[62:63] offset:16 nt
	s_add_u32 s62, s62, 0x8000
	s_addc_u32 s63, s63, 0
	global_store_dwordx4 v171, v[12:15], s[62:63] nt
	global_store_dwordx4 v171, v[8:11], s[62:63] offset:16 nt
.Lmx_10_nonv:
	v_cvt_pk_bf16_f32 v174, v60, v61
	v_cvt_pk_bf16_f32 v175, v62, v63
	v_cvt_pk_bf16_f32 v176, v56, v57
	v_cvt_pk_bf16_f32 v177, v58, v59
	v_mov_b32_dpp v230, v174 quad_perm:[1,0,3,2] row_mask:0xf bank_mask:0xf
	v_mov_b32_dpp v231, v175 quad_perm:[1,0,3,2] row_mask:0xf bank_mask:0xf
	v_mov_b32_dpp v232, v176 quad_perm:[1,0,3,2] row_mask:0xf bank_mask:0xf
	v_mov_b32_dpp v233, v177 quad_perm:[1,0,3,2] row_mask:0xf bank_mask:0xf
	v_perm_b32 v230, v230, v174, v238
	v_perm_b32 v231, v231, v175, v238
	v_perm_b32 v232, v232, v176, v238
	v_perm_b32 v233, v233, v177, v238
	ds_write_b32 v239, v230 offset:0
	ds_write_b32 v239, v231 offset:272
	ds_write_b32 v239, v232 offset:544
	ds_write_b32 v239, v233 offset:816
	v_cvt_pk_bf16_f32 v178, v44, v45
	v_cvt_pk_bf16_f32 v179, v46, v47
	v_cvt_pk_bf16_f32 v180, v40, v41
	v_cvt_pk_bf16_f32 v181, v42, v43
	v_mov_b32_dpp v234, v178 quad_perm:[1,0,3,2] row_mask:0xf bank_mask:0xf
	v_mov_b32_dpp v235, v179 quad_perm:[1,0,3,2] row_mask:0xf bank_mask:0xf
	v_mov_b32_dpp v236, v180 quad_perm:[1,0,3,2] row_mask:0xf bank_mask:0xf
	v_mov_b32_dpp v237, v181 quad_perm:[1,0,3,2] row_mask:0xf bank_mask:0xf
	v_perm_b32 v234, v234, v178, v238
	v_perm_b32 v235, v235, v179, v238
	v_perm_b32 v236, v236, v180, v238
	v_perm_b32 v237, v237, v181, v238
	ds_write_b32 v239, v234 offset:32
	ds_write_b32 v239, v235 offset:304
	ds_write_b32 v239, v236 offset:576
	ds_write_b32 v239, v237 offset:848
	v_cvt_pk_bf16_f32 v174, v28, v29
	v_cvt_pk_bf16_f32 v175, v30, v31
	v_cvt_pk_bf16_f32 v176, v24, v25
	v_cvt_pk_bf16_f32 v177, v26, v27
	v_mov_b32_dpp v230, v174 quad_perm:[1,0,3,2] row_mask:0xf bank_mask:0xf
	v_mov_b32_dpp v231, v175 quad_perm:[1,0,3,2] row_mask:0xf bank_mask:0xf
	v_mov_b32_dpp v232, v176 quad_perm:[1,0,3,2] row_mask:0xf bank_mask:0xf
	v_mov_b32_dpp v233, v177 quad_perm:[1,0,3,2] row_mask:0xf bank_mask:0xf
	v_perm_b32 v230, v230, v174, v238
	v_perm_b32 v231, v231, v175, v238
	v_perm_b32 v232, v232, v176, v238
	v_perm_b32 v233, v233, v177, v238
	ds_write_b32 v239, v230 offset:64
	ds_write_b32 v239, v231 offset:336
	ds_write_b32 v239, v232 offset:608
	ds_write_b32 v239, v233 offset:880
	v_cvt_pk_bf16_f32 v178, v12, v13
	v_cvt_pk_bf16_f32 v179, v14, v15
	v_cvt_pk_bf16_f32 v180, v8, v9
	v_cvt_pk_bf16_f32 v181, v10, v11
	v_mov_b32_dpp v234, v178 quad_perm:[1,0,3,2] row_mask:0xf bank_mask:0xf
	v_mov_b32_dpp v235, v179 quad_perm:[1,0,3,2] row_mask:0xf bank_mask:0xf
	v_mov_b32_dpp v236, v180 quad_perm:[1,0,3,2] row_mask:0xf bank_mask:0xf
	v_mov_b32_dpp v237, v181 quad_perm:[1,0,3,2] row_mask:0xf bank_mask:0xf
	v_perm_b32 v234, v234, v178, v238
	v_perm_b32 v235, v235, v179, v238
	v_perm_b32 v236, v236, v180, v238
	v_perm_b32 v237, v237, v181, v238
	ds_write_b32 v239, v234 offset:96
	ds_write_b32 v239, v235 offset:368
	ds_write_b32 v239, v236 offset:640
	ds_write_b32 v239, v237 offset:912
	s_waitcnt lgkmcnt(0)
	ds_read_b64 v[214:215], v169 offset:0
	ds_read_b64 v[216:217], v169 offset:8
	ds_read_b64 v[218:219], v169 offset:1088
	ds_read_b64 v[220:221], v169 offset:1096
	ds_read_b64 v[222:223], v169 offset:2176
	ds_read_b64 v[224:225], v169 offset:2184
	ds_read_b64 v[226:227], v169 offset:3264
	ds_read_b64 v[228:229], v169 offset:3272
	s_mov_b64 s[62:63], s[58:59]
	s_add_u32 s62, s62, s55
	s_addc_u32 s63, s63, 0
	s_waitcnt lgkmcnt(6)
	global_store_dwordx4 v170, v[214:217], s[62:63] sc1
	s_add_u32 s62, s62, s100
	s_addc_u32 s63, s63, 0
	s_waitcnt lgkmcnt(4)
	global_store_dwordx4 v170, v[218:221], s[62:63] sc1
	s_add_u32 s62, s62, s100
	s_addc_u32 s63, s63, 0
	s_waitcnt lgkmcnt(2)
	global_store_dwordx4 v170, v[222:225], s[62:63] sc1
	s_add_u32 s62, s62, s100
	s_addc_u32 s63, s63, 0
	s_waitcnt lgkmcnt(0)
	global_store_dwordx4 v170, v[226:229], s[62:63] sc1
	s_cmp_eq_u32 s95, 0
	s_cbranch_scc1 .Lmx_11_nonv
	s_add_u32 s62, s60, 0x40200
	s_addc_u32 s63, s61, 0
	global_store_dwordx4 v171, v[52:55], s[62:63] nt
	global_store_dwordx4 v171, v[48:51], s[62:63] offset:16 nt
	s_add_u32 s62, s62, 0x8000
	s_addc_u32 s63, s63, 0
	global_store_dwordx4 v171, v[36:39], s[62:63] nt
	global_store_dwordx4 v171, v[32:35], s[62:63] offset:16 nt
	s_add_u32 s62, s62, 0x8000
	s_addc_u32 s63, s63, 0
	global_store_dwordx4 v171, v[20:23], s[62:63] nt
	global_store_dwordx4 v171, v[16:19], s[62:63] offset:16 nt
	s_add_u32 s62, s62, 0x8000
	s_addc_u32 s63, s63, 0
	global_store_dwordx4 v171, v[4:7], s[62:63] nt
	global_store_dwordx4 v171, v[0:3], s[62:63] offset:16 nt
.Lmx_11_nonv:
	v_cvt_pk_bf16_f32 v174, v52, v53
	v_cvt_pk_bf16_f32 v175, v54, v55
	v_cvt_pk_bf16_f32 v176, v48, v49
	v_cvt_pk_bf16_f32 v177, v50, v51
	v_mov_b32_dpp v230, v174 quad_perm:[1,0,3,2] row_mask:0xf bank_mask:0xf
	v_mov_b32_dpp v231, v175 quad_perm:[1,0,3,2] row_mask:0xf bank_mask:0xf
	v_mov_b32_dpp v232, v176 quad_perm:[1,0,3,2] row_mask:0xf bank_mask:0xf
	v_mov_b32_dpp v233, v177 quad_perm:[1,0,3,2] row_mask:0xf bank_mask:0xf
	v_perm_b32 v230, v230, v174, v238
	v_perm_b32 v231, v231, v175, v238
	v_perm_b32 v232, v232, v176, v238
	v_perm_b32 v233, v233, v177, v238
	ds_write_b32 v239, v230 offset:0
	ds_write_b32 v239, v231 offset:272
	ds_write_b32 v239, v232 offset:544
	ds_write_b32 v239, v233 offset:816
	v_cvt_pk_bf16_f32 v178, v36, v37
	v_cvt_pk_bf16_f32 v179, v38, v39
	v_cvt_pk_bf16_f32 v180, v32, v33
	v_cvt_pk_bf16_f32 v181, v34, v35
	v_mov_b32_dpp v234, v178 quad_perm:[1,0,3,2] row_mask:0xf bank_mask:0xf
	v_mov_b32_dpp v235, v179 quad_perm:[1,0,3,2] row_mask:0xf bank_mask:0xf
	v_mov_b32_dpp v236, v180 quad_perm:[1,0,3,2] row_mask:0xf bank_mask:0xf
	v_mov_b32_dpp v237, v181 quad_perm:[1,0,3,2] row_mask:0xf bank_mask:0xf
	v_perm_b32 v234, v234, v178, v238
	v_perm_b32 v235, v235, v179, v238
	v_perm_b32 v236, v236, v180, v238
	v_perm_b32 v237, v237, v181, v238
	ds_write_b32 v239, v234 offset:32
	ds_write_b32 v239, v235 offset:304
	ds_write_b32 v239, v236 offset:576
	ds_write_b32 v239, v237 offset:848
	v_cvt_pk_bf16_f32 v174, v20, v21
	v_cvt_pk_bf16_f32 v175, v22, v23
	v_cvt_pk_bf16_f32 v176, v16, v17
	v_cvt_pk_bf16_f32 v177, v18, v19
	v_mov_b32_dpp v230, v174 quad_perm:[1,0,3,2] row_mask:0xf bank_mask:0xf
	v_mov_b32_dpp v231, v175 quad_perm:[1,0,3,2] row_mask:0xf bank_mask:0xf
	v_mov_b32_dpp v232, v176 quad_perm:[1,0,3,2] row_mask:0xf bank_mask:0xf
	v_mov_b32_dpp v233, v177 quad_perm:[1,0,3,2] row_mask:0xf bank_mask:0xf
	v_perm_b32 v230, v230, v174, v238
	v_perm_b32 v231, v231, v175, v238
	v_perm_b32 v232, v232, v176, v238
	v_perm_b32 v233, v233, v177, v238
	ds_write_b32 v239, v230 offset:64
	ds_write_b32 v239, v231 offset:336
	ds_write_b32 v239, v232 offset:608
	ds_write_b32 v239, v233 offset:880
	v_cvt_pk_bf16_f32 v178, v4, v5
	v_cvt_pk_bf16_f32 v179, v6, v7
	v_cvt_pk_bf16_f32 v180, v0, v1
	v_cvt_pk_bf16_f32 v181, v2, v3
	v_mov_b32_dpp v234, v178 quad_perm:[1,0,3,2] row_mask:0xf bank_mask:0xf
	v_mov_b32_dpp v235, v179 quad_perm:[1,0,3,2] row_mask:0xf bank_mask:0xf
	v_mov_b32_dpp v236, v180 quad_perm:[1,0,3,2] row_mask:0xf bank_mask:0xf
	v_mov_b32_dpp v237, v181 quad_perm:[1,0,3,2] row_mask:0xf bank_mask:0xf
	v_perm_b32 v234, v234, v178, v238
	v_perm_b32 v235, v235, v179, v238
	v_perm_b32 v236, v236, v180, v238
	v_perm_b32 v237, v237, v181, v238
	ds_write_b32 v239, v234 offset:96
	ds_write_b32 v239, v235 offset:368
	ds_write_b32 v239, v236 offset:640
	ds_write_b32 v239, v237 offset:912
	s_waitcnt lgkmcnt(0)
	ds_read_b64 v[214:215], v169 offset:0
	ds_read_b64 v[216:217], v169 offset:8
	ds_read_b64 v[218:219], v169 offset:1088
	ds_read_b64 v[220:221], v169 offset:1096
	ds_read_b64 v[222:223], v169 offset:2176
	ds_read_b64 v[224:225], v169 offset:2184
	ds_read_b64 v[226:227], v169 offset:3264
	ds_read_b64 v[228:229], v169 offset:3272
	s_mov_b64 s[62:63], s[58:59]
	s_add_u32 s62, s62, s55
	s_addc_u32 s63, s63, 0
	s_add_u32 s62, s62, s73
	s_addc_u32 s63, s63, 0
	s_waitcnt lgkmcnt(6)
	global_store_dwordx4 v170, v[214:217], s[62:63] sc1
	s_add_u32 s62, s62, s100
	s_addc_u32 s63, s63, 0
	s_waitcnt lgkmcnt(4)
	global_store_dwordx4 v170, v[218:221], s[62:63] sc1
	s_add_u32 s62, s62, s100
	s_addc_u32 s63, s63, 0
	s_waitcnt lgkmcnt(2)
	global_store_dwordx4 v170, v[222:225], s[62:63] sc1
	s_add_u32 s62, s62, s100
	s_addc_u32 s63, s63, 0
	s_waitcnt lgkmcnt(0)
	global_store_dwordx4 v170, v[226:229], s[62:63] sc1
	s_branch .LBB0_917
.Ltramp_334:
	s_branch .LBB0_334
.Ltramp_333:
	s_branch .LBB0_333
.LBB0_920:
	s_waitcnt vmcnt(0)
	v_readlane_b32 s82, v255, 6
	v_readlane_b32 s84, v255, 8
	v_readlane_b32 s92, v255, 10
	v_readlane_b32 s83, v255, 7
	v_readlane_b32 s85, v255, 9
	v_readlane_b32 s93, v255, 11
	s_movk_i32 s67, 0x1000
	s_movk_i32 s69, 0xfff
	s_mov_b32 s73, 0xff000000
	s_mov_b64 s[94:95], 0x1000
	s_mov_b32 s74, 0xf7800000
	s_movk_i32 s75, 0x1fff
	s_mov_b32 s76, 0x10000
	s_mov_b32 s77, 0x18000
	s_mov_b32 s86, 0x8000
	s_mov_b32 s87, 0x40000
	s_mov_b32 s90, 0x48000
	s_mov_b32 s78, 0x50000
	s_mov_b32 s79, 0x58000
	s_barrier
